# grid barrier: waiters poll the cross-die arrival counter against (generation+1)*dies instead of a separate generation word
# baseline (speedup 1.0000x reference)
; __device__ __forceinline__ unsigned xb_ld(unsigned* p)              { return __hip_atomic_load(p, __ATOMIC_RELAXED, __HIP_MEMORY_SCOPE_AGENT); }
; __device__ __forceinline__ unsigned xb_add(unsigned* p, unsigned v) { return __hip_atomic_fetch_add(p, v, __ATOMIC_RELAXED, __HIP_MEMORY_SCOPE_AGENT); }
; #define XB_SPIN(cond, bar) do { unsigned _sp = 0; while (cond) { __builtin_amdgcn_s_sleep(1); \
;     if ((++_sp & 255u) == 0u) { if (xb_ld(&(bar)[XB_TMO])) break; if (_sp > XB_SPIN_CAP) { atomicAdd(&(bar)[XB_TMO], 1u); break; } } } } while (0)
; __device__ __forceinline__ void xcd_barrier(const XcdBarrier& b) {
;     ...
;         const unsigned old = xb_add(&bar[XB_XSUB(b.x)], 1u);
;         const unsigned gen = old / nloc;
;         if (old + 1u == (gen + 1u) * nloc) {
;             __builtin_amdgcn_fence(__ATOMIC_RELEASE, "agent");
;             asm volatile("s_waitcnt vmcnt(0)" ::: "memory");
;             const unsigned og = xb_add(&bar[XB_TOP], 1u);
;             const unsigned tg = og / nx;
;             if (og + 1u == (tg + 1u) * nx) xb_add(&bar[XB_TOPGEN], 1u);
;             else XB_SPIN(xb_ld(&bar[XB_TOPGEN]) == tg, bar);
;             __builtin_amdgcn_fence(__ATOMIC_ACQUIRE, "agent");
;             xb_add(&bar[XB_XGEN(b.x)], 1u);
;             asm volatile("s_waitcnt vmcnt(0)" ::: "memory");
;         } else {
;             XB_SPIN(xb_ld(&bar[XB_XGEN(b.x)]) == gen, bar);
.LBB0_51:
	s_or_b64 exec, exec, s[18:19]
	v_cvt_f32_u32_e32 v4, v2
	s_waitcnt vmcnt(0)
	v_readfirstlane_b32 s3, v3
	v_sub_u32_e32 v3, 0, v2
	v_rcp_iflag_f32_e32 v4, v4
	v_add_u32_e32 v5, s3, v1
	v_mul_f32_e32 v4, 0x4f7ffffe, v4
	v_cvt_u32_f32_e32 v4, v4
	v_mul_lo_u32 v1, v3, v4
	v_mul_hi_u32 v1, v4, v1
	v_add_u32_e32 v1, v4, v1
	v_mul_hi_u32 v1, v5, v1
	v_mul_lo_u32 v3, v1, v2
	v_sub_u32_e32 v3, v5, v3
	v_add_u32_e32 v4, 1, v1
	v_sub_u32_e32 v6, v3, v2
	v_cmp_ge_u32_e32 vcc, v3, v2
	s_nop 1
	v_cndmask_b32_e32 v1, v1, v4, vcc
	v_cndmask_b32_e32 v3, v3, v6, vcc
	v_add_u32_e32 v4, 1, v1
	v_cmp_ge_u32_e32 vcc, v3, v2
	v_add_u32_e32 v3, 1, v5
	s_nop 0
	v_cndmask_b32_e32 v1, v1, v4, vcc
	v_mul_lo_u32 v4, v2, v1
	v_add_u32_e32 v2, v4, v2
	v_cmp_ne_u32_e32 vcc, v3, v2
	s_and_saveexec_b64 s[16:17], vcc
	s_xor_b64 s[18:19], exec, s[16:17]
	s_cbranch_execz .LBB0_65
	s_waitcnt lgkmcnt(0)
	v_add_u32_e32 v1, 1, v1
	v_mul_lo_u32 v1, v1, v0
	v_mov_b32_e32 v0, 0
	global_load_dword v2, v0, s[26:27] offset:-256 sc1
	s_waitcnt vmcnt(0)
	v_cmp_gt_u32_e32 vcc, v1, v2
	s_and_saveexec_b64 s[20:21], vcc
	s_cbranch_execz .LBB0_64
	s_mov_b32 s3, 1
	s_mov_b64 s[22:23], 0
	s_branch .LBB0_55

; __device__ __forceinline__ unsigned xb_ld(unsigned* p)              { return __hip_atomic_load(p, __ATOMIC_RELAXED, __HIP_MEMORY_SCOPE_AGENT); }
; #define XB_SPIN(cond, bar) do { unsigned _sp = 0; while (cond) { __builtin_amdgcn_s_sleep(1); \
;     if ((++_sp & 255u) == 0u) { if (xb_ld(&(bar)[XB_TMO])) break; if (_sp > XB_SPIN_CAP) { atomicAdd(&(bar)[XB_TMO], 1u); break; } } } } while (0)
; __device__ __forceinline__ void xcd_barrier(const XcdBarrier& b) {
;     ...
;             XB_SPIN(xb_ld(&bar[XB_XGEN(b.x)]) == gen, bar);
.LBB0_57:
	global_load_dword v2, v0, s[26:27] offset:-256 sc1
	s_add_i32 s3, s3, 1
	s_mov_b64 s[40:41], -1
	s_waitcnt vmcnt(0)
	v_cmp_le_u32_e32 vcc, v1, v2
	s_orn2_b64 s[38:39], vcc, exec
	s_branch .LBB0_54

; __device__ __forceinline__ unsigned xb_ld(unsigned* p)              { return __hip_atomic_load(p, __ATOMIC_RELAXED, __HIP_MEMORY_SCOPE_AGENT); }
; __device__ __forceinline__ unsigned xb_add(unsigned* p, unsigned v) { return __hip_atomic_fetch_add(p, v, __ATOMIC_RELAXED, __HIP_MEMORY_SCOPE_AGENT); }
; #define XB_SPIN(cond, bar) do { unsigned _sp = 0; while (cond) { __builtin_amdgcn_s_sleep(1); \
;     if ((++_sp & 255u) == 0u) { if (xb_ld(&(bar)[XB_TMO])) break; if (_sp > XB_SPIN_CAP) { atomicAdd(&(bar)[XB_TMO], 1u); break; } } } } while (0)
; __device__ __forceinline__ void xcd_barrier(const XcdBarrier& b) {
;     ...
;             const unsigned og = xb_add(&bar[XB_TOP], 1u);
;             const unsigned tg = og / nx;
;             if (og + 1u == (tg + 1u) * nx) xb_add(&bar[XB_TOPGEN], 1u);
;             else XB_SPIN(xb_ld(&bar[XB_TOPGEN]) == tg, bar);
.LBB0_68:
	s_or_b64 exec, exec, s[20:21]
	v_cvt_f32_u32_e32 v3, v0
	s_waitcnt vmcnt(0)
	v_readfirstlane_b32 s3, v2
	v_sub_u32_e32 v2, 0, v0
	s_mov_b64 s[20:21], -1
	v_rcp_iflag_f32_e32 v3, v3
	v_add_u32_e32 v1, s3, v1
	v_add_u32_e32 v4, 1, v1
	v_mul_f32_e32 v3, 0x4f7ffffe, v3
	v_cvt_u32_f32_e32 v3, v3
	v_mul_lo_u32 v2, v2, v3
	v_mul_hi_u32 v2, v3, v2
	v_add_u32_e32 v2, v3, v2
	v_mul_hi_u32 v2, v1, v2
	v_mul_lo_u32 v3, v2, v0
	v_sub_u32_e32 v1, v1, v3
	v_add_u32_e32 v5, 1, v2
	v_sub_u32_e32 v3, v1, v0
	v_cmp_ge_u32_e32 vcc, v1, v0
	s_nop 1
	v_cndmask_b32_e32 v2, v2, v5, vcc
	v_cndmask_b32_e32 v1, v1, v3, vcc
	v_add_u32_e32 v3, 1, v2
	v_cmp_ge_u32_e32 vcc, v1, v0
	s_nop 1
	v_cndmask_b32_e32 v2, v2, v3, vcc
	v_mul_lo_u32 v1, v0, v2
	v_add_u32_e32 v0, v1, v0
	v_cmp_ne_u32_e32 vcc, v4, v0
	v_mov_b32_e32 v250, v0
	v_mov_b64_e32 v[0:1], s[26:27]
	s_and_saveexec_b64 s[18:19], vcc
	s_cbranch_execz .LBB0_80
	v_mov_b32_e32 v0, 0
	global_load_dword v1, v0, s[26:27] offset:-256 sc1
	s_mov_b64 s[22:23], 0
	s_waitcnt vmcnt(0)
	v_cmp_gt_u32_e32 vcc, v250, v1
	s_and_saveexec_b64 s[20:21], vcc
	s_cbranch_execz .LBB0_79
	s_mov_b32 s3, 1
	s_branch .LBB0_72

; __device__ __forceinline__ unsigned xb_ld(unsigned* p)              { return __hip_atomic_load(p, __ATOMIC_RELAXED, __HIP_MEMORY_SCOPE_AGENT); }
; #define XB_SPIN(cond, bar) do { unsigned _sp = 0; while (cond) { __builtin_amdgcn_s_sleep(1); \
;     if ((++_sp & 255u) == 0u) { if (xb_ld(&(bar)[XB_TMO])) break; if (_sp > XB_SPIN_CAP) { atomicAdd(&(bar)[XB_TMO], 1u); break; } } } } while (0)
; __device__ __forceinline__ void xcd_barrier(const XcdBarrier& b) {
;     ...
;             else XB_SPIN(xb_ld(&bar[XB_TOPGEN]) == tg, bar);
.LBB0_74:
	global_load_dword v1, v0, s[26:27] offset:-256 sc1
	s_add_i32 s3, s3, 1
	s_mov_b64 s[38:39], -1
	s_waitcnt vmcnt(0)
	v_cmp_le_u32_e32 vcc, v250, v1
	s_orn2_b64 s[42:43], vcc, exec
	s_branch .LBB0_71

; __device__ __forceinline__ unsigned xb_ld(unsigned* p)              { return __hip_atomic_load(p, __ATOMIC_RELAXED, __HIP_MEMORY_SCOPE_AGENT); }
; __device__ __forceinline__ unsigned xb_add(unsigned* p, unsigned v) { return __hip_atomic_fetch_add(p, v, __ATOMIC_RELAXED, __HIP_MEMORY_SCOPE_AGENT); }
; #define XB_SPIN(cond, bar) do { unsigned _sp = 0; while (cond) { __builtin_amdgcn_s_sleep(1); \
;     if ((++_sp & 255u) == 0u) { if (xb_ld(&(bar)[XB_TMO])) break; if (_sp > XB_SPIN_CAP) { atomicAdd(&(bar)[XB_TMO], 1u); break; } } } } while (0)
; __device__ __forceinline__ void xcd_barrier(const XcdBarrier& b) {
;     ...
;         const unsigned old = xb_add(&bar[XB_XSUB(b.x)], 1u);
;         const unsigned gen = old / nloc;
;         if (old + 1u == (gen + 1u) * nloc) {
;             __builtin_amdgcn_fence(__ATOMIC_RELEASE, "agent");
;             asm volatile("s_waitcnt vmcnt(0)" ::: "memory");
;             const unsigned og = xb_add(&bar[XB_TOP], 1u);
;             const unsigned tg = og / nx;
;             if (og + 1u == (tg + 1u) * nx) xb_add(&bar[XB_TOPGEN], 1u);
;             else XB_SPIN(xb_ld(&bar[XB_TOPGEN]) == tg, bar);
;             __builtin_amdgcn_fence(__ATOMIC_ACQUIRE, "agent");
;             xb_add(&bar[XB_XGEN(b.x)], 1u);
;             asm volatile("s_waitcnt vmcnt(0)" ::: "memory");
;         } else {
;             XB_SPIN(xb_ld(&bar[XB_XGEN(b.x)]) == gen, bar);
.LBB0_182:
	s_or_b64 exec, exec, s[18:19]
	v_cvt_f32_u32_e32 v4, v2
	s_waitcnt vmcnt(0)
	v_readfirstlane_b32 s5, v3
	v_sub_u32_e32 v3, 0, v2
	v_rcp_iflag_f32_e32 v4, v4
	v_add_u32_e32 v5, s5, v1
	v_mul_f32_e32 v4, 0x4f7ffffe, v4
	v_cvt_u32_f32_e32 v4, v4
	v_mul_lo_u32 v1, v3, v4
	v_mul_hi_u32 v1, v4, v1
	v_add_u32_e32 v1, v4, v1
	v_mul_hi_u32 v1, v5, v1
	v_mul_lo_u32 v3, v1, v2
	v_sub_u32_e32 v3, v5, v3
	v_add_u32_e32 v4, 1, v1
	v_cmp_ge_u32_e32 vcc, v3, v2
	s_nop 1
	v_cndmask_b32_e32 v1, v1, v4, vcc
	v_sub_u32_e32 v4, v3, v2
	v_cndmask_b32_e32 v3, v3, v4, vcc
	v_add_u32_e32 v4, 1, v1
	v_cmp_ge_u32_e32 vcc, v3, v2
	v_add_u32_e32 v3, 1, v5
	s_nop 0
	v_cndmask_b32_e32 v1, v1, v4, vcc
	v_mul_lo_u32 v4, v2, v1
	v_add_u32_e32 v2, v4, v2
	v_cmp_ne_u32_e32 vcc, v3, v2
	s_and_saveexec_b64 s[14:15], vcc
	s_xor_b64 s[18:19], exec, s[14:15]
	s_cbranch_execz .LBB0_196
	s_waitcnt lgkmcnt(0)
	v_add_u32_e32 v1, 1, v1
	v_mul_lo_u32 v1, v1, v0
	v_mov_b32_e32 v0, 0
	global_load_dword v2, v0, s[26:27] offset:-256 sc1
	s_waitcnt vmcnt(0)
	v_cmp_gt_u32_e32 vcc, v1, v2
	s_and_saveexec_b64 s[22:23], vcc
	s_cbranch_execz .LBB0_195
	s_mov_b32 s5, 1
	s_mov_b64 s[36:37], 0
	s_branch .LBB0_186

; __device__ __forceinline__ unsigned xb_ld(unsigned* p)              { return __hip_atomic_load(p, __ATOMIC_RELAXED, __HIP_MEMORY_SCOPE_AGENT); }
; #define XB_SPIN(cond, bar) do { unsigned _sp = 0; while (cond) { __builtin_amdgcn_s_sleep(1); \
;     if ((++_sp & 255u) == 0u) { if (xb_ld(&(bar)[XB_TMO])) break; if (_sp > XB_SPIN_CAP) { atomicAdd(&(bar)[XB_TMO], 1u); break; } } } } while (0)
; __device__ __forceinline__ void xcd_barrier(const XcdBarrier& b) {
;     ...
;             XB_SPIN(xb_ld(&bar[XB_XGEN(b.x)]) == gen, bar);
.LBB0_188:
	global_load_dword v2, v0, s[26:27] offset:-256 sc1
	s_add_i32 s5, s5, 1
	s_mov_b64 s[42:43], -1
	s_waitcnt vmcnt(0)
	v_cmp_le_u32_e32 vcc, v1, v2
	s_orn2_b64 s[40:41], vcc, exec
	s_branch .LBB0_185

; __device__ __forceinline__ unsigned xb_ld(unsigned* p)              { return __hip_atomic_load(p, __ATOMIC_RELAXED, __HIP_MEMORY_SCOPE_AGENT); }
; __device__ __forceinline__ unsigned xb_add(unsigned* p, unsigned v) { return __hip_atomic_fetch_add(p, v, __ATOMIC_RELAXED, __HIP_MEMORY_SCOPE_AGENT); }
; #define XB_SPIN(cond, bar) do { unsigned _sp = 0; while (cond) { __builtin_amdgcn_s_sleep(1); \
;     if ((++_sp & 255u) == 0u) { if (xb_ld(&(bar)[XB_TMO])) break; if (_sp > XB_SPIN_CAP) { atomicAdd(&(bar)[XB_TMO], 1u); break; } } } } while (0)
; __device__ __forceinline__ void xcd_barrier(const XcdBarrier& b) {
;     ...
;             const unsigned og = xb_add(&bar[XB_TOP], 1u);
;             const unsigned tg = og / nx;
;             if (og + 1u == (tg + 1u) * nx) xb_add(&bar[XB_TOPGEN], 1u);
;             else XB_SPIN(xb_ld(&bar[XB_TOPGEN]) == tg, bar);
.LBB0_199:
	s_or_b64 exec, exec, s[22:23]
	s_waitcnt vmcnt(0)
	v_readfirstlane_b32 s5, v2
	v_cvt_f32_u32_e32 v2, v0
	v_sub_u32_e32 v3, 0, v0
	v_add_u32_e32 v1, s5, v1
	s_mov_b64 s[22:23], -1
	v_rcp_iflag_f32_e32 v2, v2
	s_nop 0
	v_mul_f32_e32 v2, 0x4f7ffffe, v2
	v_cvt_u32_f32_e32 v2, v2
	v_mul_lo_u32 v3, v3, v2
	v_mul_hi_u32 v3, v2, v3
	v_add_u32_e32 v2, v2, v3
	v_mul_hi_u32 v2, v1, v2
	v_mul_lo_u32 v3, v2, v0
	v_sub_u32_e32 v3, v1, v3
	v_cmp_ge_u32_e32 vcc, v3, v0
	v_add_u32_e32 v4, 1, v2
	v_add_u32_e32 v1, 1, v1
	v_cndmask_b32_e32 v2, v2, v4, vcc
	v_sub_u32_e32 v4, v3, v0
	v_cndmask_b32_e32 v3, v3, v4, vcc
	v_cmp_ge_u32_e32 vcc, v3, v0
	v_add_u32_e32 v3, 1, v2
	s_nop 0
	v_cndmask_b32_e32 v2, v2, v3, vcc
	v_mul_lo_u32 v3, v0, v2
	v_add_u32_e32 v0, v3, v0
	v_cmp_ne_u32_e32 vcc, v1, v0
	v_mov_b32_e32 v250, v0
	v_mov_b64_e32 v[0:1], s[26:27]
	s_and_saveexec_b64 s[18:19], vcc
	s_cbranch_execz .LBB0_211
	v_mov_b32_e32 v0, 0
	global_load_dword v1, v0, s[26:27] offset:-256 sc1
	s_mov_b64 s[36:37], 0
	s_waitcnt vmcnt(0)
	v_cmp_gt_u32_e32 vcc, v250, v1
	s_and_saveexec_b64 s[22:23], vcc
	s_cbranch_execz .LBB0_210
	s_mov_b32 s5, 1
	s_branch .LBB0_203

; __device__ __forceinline__ unsigned xb_ld(unsigned* p)              { return __hip_atomic_load(p, __ATOMIC_RELAXED, __HIP_MEMORY_SCOPE_AGENT); }
; #define XB_SPIN(cond, bar) do { unsigned _sp = 0; while (cond) { __builtin_amdgcn_s_sleep(1); \
;     if ((++_sp & 255u) == 0u) { if (xb_ld(&(bar)[XB_TMO])) break; if (_sp > XB_SPIN_CAP) { atomicAdd(&(bar)[XB_TMO], 1u); break; } } } } while (0)
; __device__ __forceinline__ void xcd_barrier(const XcdBarrier& b) {
;     ...
;             else XB_SPIN(xb_ld(&bar[XB_TOPGEN]) == tg, bar);
.LBB0_205:
	global_load_dword v1, v0, s[26:27] offset:-256 sc1
	s_add_i32 s5, s5, 1
	s_mov_b64 s[40:41], -1
	s_waitcnt vmcnt(0)
	v_cmp_le_u32_e32 vcc, v250, v1
	s_orn2_b64 s[44:45], vcc, exec
	s_branch .LBB0_202

; __device__ __forceinline__ unsigned xb_ld(unsigned* p)              { return __hip_atomic_load(p, __ATOMIC_RELAXED, __HIP_MEMORY_SCOPE_AGENT); }
; __device__ __forceinline__ unsigned xb_add(unsigned* p, unsigned v) { return __hip_atomic_fetch_add(p, v, __ATOMIC_RELAXED, __HIP_MEMORY_SCOPE_AGENT); }
; #define XB_SPIN(cond, bar) do { unsigned _sp = 0; while (cond) { __builtin_amdgcn_s_sleep(1); \
;     if ((++_sp & 255u) == 0u) { if (xb_ld(&(bar)[XB_TMO])) break; if (_sp > XB_SPIN_CAP) { atomicAdd(&(bar)[XB_TMO], 1u); break; } } } } while (0)
; __device__ __forceinline__ void xcd_barrier(const XcdBarrier& b) {
;     ...
;         const unsigned old = xb_add(&bar[XB_XSUB(b.x)], 1u);
;         const unsigned gen = old / nloc;
;         if (old + 1u == (gen + 1u) * nloc) {
;             __builtin_amdgcn_fence(__ATOMIC_RELEASE, "agent");
;             asm volatile("s_waitcnt vmcnt(0)" ::: "memory");
;             const unsigned og = xb_add(&bar[XB_TOP], 1u);
;             const unsigned tg = og / nx;
;             if (og + 1u == (tg + 1u) * nx) xb_add(&bar[XB_TOPGEN], 1u);
;             else XB_SPIN(xb_ld(&bar[XB_TOPGEN]) == tg, bar);
;             __builtin_amdgcn_fence(__ATOMIC_ACQUIRE, "agent");
;             xb_add(&bar[XB_XGEN(b.x)], 1u);
;             asm volatile("s_waitcnt vmcnt(0)" ::: "memory");
;         } else {
;             XB_SPIN(xb_ld(&bar[XB_XGEN(b.x)]) == gen, bar);
.LBB0_421:
	s_or_b64 exec, exec, s[18:19]
	v_cvt_f32_u32_e32 v4, v2
	s_waitcnt vmcnt(0)
	v_readfirstlane_b32 s5, v3
	v_sub_u32_e32 v3, 0, v2
	v_rcp_iflag_f32_e32 v4, v4
	v_add_u32_e32 v5, s5, v1
	v_mul_f32_e32 v4, 0x4f7ffffe, v4
	v_cvt_u32_f32_e32 v4, v4
	v_mul_lo_u32 v1, v3, v4
	v_mul_hi_u32 v1, v4, v1
	v_add_u32_e32 v1, v4, v1
	v_mul_hi_u32 v1, v5, v1
	v_mul_lo_u32 v3, v1, v2
	v_sub_u32_e32 v3, v5, v3
	v_add_u32_e32 v4, 1, v1
	v_cmp_ge_u32_e32 vcc, v3, v2
	s_nop 1
	v_cndmask_b32_e32 v1, v1, v4, vcc
	v_sub_u32_e32 v4, v3, v2
	v_cndmask_b32_e32 v3, v3, v4, vcc
	v_add_u32_e32 v4, 1, v1
	v_cmp_ge_u32_e32 vcc, v3, v2
	v_add_u32_e32 v3, 1, v5
	s_nop 0
	v_cndmask_b32_e32 v1, v1, v4, vcc
	v_mul_lo_u32 v4, v2, v1
	v_add_u32_e32 v2, v4, v2
	v_cmp_ne_u32_e32 vcc, v3, v2
	s_and_saveexec_b64 s[14:15], vcc
	s_xor_b64 s[18:19], exec, s[14:15]
	s_cbranch_execz .LBB0_435
	s_waitcnt lgkmcnt(0)
	v_add_u32_e32 v1, 1, v1
	v_mul_lo_u32 v1, v1, v0
	v_mov_b32_e32 v0, 0
	global_load_dword v2, v0, s[26:27] offset:-256 sc1
	s_waitcnt vmcnt(0)
	v_cmp_gt_u32_e32 vcc, v1, v2
	s_and_saveexec_b64 s[36:37], vcc
	s_cbranch_execz .LBB0_434
	s_mov_b32 s5, 1
	s_mov_b64 s[38:39], 0
	s_branch .LBB0_425

; __device__ __forceinline__ unsigned xb_ld(unsigned* p)              { return __hip_atomic_load(p, __ATOMIC_RELAXED, __HIP_MEMORY_SCOPE_AGENT); }
; #define XB_SPIN(cond, bar) do { unsigned _sp = 0; while (cond) { __builtin_amdgcn_s_sleep(1); \
;     if ((++_sp & 255u) == 0u) { if (xb_ld(&(bar)[XB_TMO])) break; if (_sp > XB_SPIN_CAP) { atomicAdd(&(bar)[XB_TMO], 1u); break; } } } } while (0)
; __device__ __forceinline__ void xcd_barrier(const XcdBarrier& b) {
;     ...
;             XB_SPIN(xb_ld(&bar[XB_XGEN(b.x)]) == gen, bar);
.LBB0_427:
	global_load_dword v2, v0, s[26:27] offset:-256 sc1
	s_add_i32 s5, s5, 1
	s_mov_b64 s[44:45], -1
	s_waitcnt vmcnt(0)
	v_cmp_le_u32_e32 vcc, v1, v2
	s_orn2_b64 s[42:43], vcc, exec
	s_branch .LBB0_424

; __device__ __forceinline__ unsigned xb_ld(unsigned* p)              { return __hip_atomic_load(p, __ATOMIC_RELAXED, __HIP_MEMORY_SCOPE_AGENT); }
; __device__ __forceinline__ unsigned xb_add(unsigned* p, unsigned v) { return __hip_atomic_fetch_add(p, v, __ATOMIC_RELAXED, __HIP_MEMORY_SCOPE_AGENT); }
; #define XB_SPIN(cond, bar) do { unsigned _sp = 0; while (cond) { __builtin_amdgcn_s_sleep(1); \
;     if ((++_sp & 255u) == 0u) { if (xb_ld(&(bar)[XB_TMO])) break; if (_sp > XB_SPIN_CAP) { atomicAdd(&(bar)[XB_TMO], 1u); break; } } } } while (0)
; __device__ __forceinline__ void xcd_barrier(const XcdBarrier& b) {
;     ...
;             const unsigned og = xb_add(&bar[XB_TOP], 1u);
;             const unsigned tg = og / nx;
;             if (og + 1u == (tg + 1u) * nx) xb_add(&bar[XB_TOPGEN], 1u);
;             else XB_SPIN(xb_ld(&bar[XB_TOPGEN]) == tg, bar);
.LBB0_438:
	s_or_b64 exec, exec, s[36:37]
	s_waitcnt vmcnt(0)
	v_readfirstlane_b32 s5, v2
	v_cvt_f32_u32_e32 v2, v0
	v_sub_u32_e32 v3, 0, v0
	v_add_u32_e32 v1, s5, v1
	s_mov_b64 s[36:37], -1
	v_rcp_iflag_f32_e32 v2, v2
	s_nop 0
	v_mul_f32_e32 v2, 0x4f7ffffe, v2
	v_cvt_u32_f32_e32 v2, v2
	v_mul_lo_u32 v3, v3, v2
	v_mul_hi_u32 v3, v2, v3
	v_add_u32_e32 v2, v2, v3
	v_mul_hi_u32 v2, v1, v2
	v_mul_lo_u32 v3, v2, v0
	v_sub_u32_e32 v3, v1, v3
	v_cmp_ge_u32_e32 vcc, v3, v0
	v_add_u32_e32 v4, 1, v2
	v_add_u32_e32 v1, 1, v1
	v_cndmask_b32_e32 v2, v2, v4, vcc
	v_sub_u32_e32 v4, v3, v0
	v_cndmask_b32_e32 v3, v3, v4, vcc
	v_cmp_ge_u32_e32 vcc, v3, v0
	v_add_u32_e32 v3, 1, v2
	s_nop 0
	v_cndmask_b32_e32 v2, v2, v3, vcc
	v_mul_lo_u32 v3, v0, v2
	v_add_u32_e32 v0, v3, v0
	v_cmp_ne_u32_e32 vcc, v1, v0
	v_mov_b32_e32 v250, v0
	v_mov_b64_e32 v[0:1], s[26:27]
	s_and_saveexec_b64 s[18:19], vcc
	s_cbranch_execz .LBB0_450
	v_mov_b32_e32 v0, 0
	global_load_dword v1, v0, s[26:27] offset:-256 sc1
	s_mov_b64 s[38:39], 0
	s_waitcnt vmcnt(0)
	v_cmp_gt_u32_e32 vcc, v250, v1
	s_and_saveexec_b64 s[36:37], vcc
	s_cbranch_execz .LBB0_449
	s_mov_b32 s5, 1
	s_branch .LBB0_442

; __device__ __forceinline__ unsigned xb_ld(unsigned* p)              { return __hip_atomic_load(p, __ATOMIC_RELAXED, __HIP_MEMORY_SCOPE_AGENT); }
; #define XB_SPIN(cond, bar) do { unsigned _sp = 0; while (cond) { __builtin_amdgcn_s_sleep(1); \
;     if ((++_sp & 255u) == 0u) { if (xb_ld(&(bar)[XB_TMO])) break; if (_sp > XB_SPIN_CAP) { atomicAdd(&(bar)[XB_TMO], 1u); break; } } } } while (0)
; __device__ __forceinline__ void xcd_barrier(const XcdBarrier& b) {
;     ...
;             else XB_SPIN(xb_ld(&bar[XB_TOPGEN]) == tg, bar);
.LBB0_444:
	global_load_dword v1, v0, s[26:27] offset:-256 sc1
	s_add_i32 s5, s5, 1
	s_mov_b64 s[42:43], -1
	s_waitcnt vmcnt(0)
	v_cmp_le_u32_e32 vcc, v250, v1
	s_orn2_b64 s[46:47], vcc, exec
	s_branch .LBB0_441

; __device__ __forceinline__ unsigned xb_ld(unsigned* p)              { return __hip_atomic_load(p, __ATOMIC_RELAXED, __HIP_MEMORY_SCOPE_AGENT); }
; __device__ __forceinline__ unsigned xb_add(unsigned* p, unsigned v) { return __hip_atomic_fetch_add(p, v, __ATOMIC_RELAXED, __HIP_MEMORY_SCOPE_AGENT); }
; #define XB_SPIN(cond, bar) do { unsigned _sp = 0; while (cond) { __builtin_amdgcn_s_sleep(1); \
;     if ((++_sp & 255u) == 0u) { if (xb_ld(&(bar)[XB_TMO])) break; if (_sp > XB_SPIN_CAP) { atomicAdd(&(bar)[XB_TMO], 1u); break; } } } } while (0)
; __device__ __forceinline__ void xcd_barrier(const XcdBarrier& b) {
;     ...
;         const unsigned old = xb_add(&bar[XB_XSUB(b.x)], 1u);
;         const unsigned gen = old / nloc;
;         if (old + 1u == (gen + 1u) * nloc) {
;             __builtin_amdgcn_fence(__ATOMIC_RELEASE, "agent");
;             asm volatile("s_waitcnt vmcnt(0)" ::: "memory");
;             const unsigned og = xb_add(&bar[XB_TOP], 1u);
;             const unsigned tg = og / nx;
;             if (og + 1u == (tg + 1u) * nx) xb_add(&bar[XB_TOPGEN], 1u);
;             else XB_SPIN(xb_ld(&bar[XB_TOPGEN]) == tg, bar);
;             __builtin_amdgcn_fence(__ATOMIC_ACQUIRE, "agent");
;             xb_add(&bar[XB_XGEN(b.x)], 1u);
;             asm volatile("s_waitcnt vmcnt(0)" ::: "memory");
;         } else {
;             XB_SPIN(xb_ld(&bar[XB_XGEN(b.x)]) == gen, bar);
.LBB0_493:
	s_or_b64 exec, exec, s[18:19]
	v_cvt_f32_u32_e32 v4, v2
	s_waitcnt vmcnt(0)
	v_readfirstlane_b32 s5, v3
	v_sub_u32_e32 v3, 0, v2
	v_rcp_iflag_f32_e32 v4, v4
	v_add_u32_e32 v5, s5, v1
	v_mul_f32_e32 v4, 0x4f7ffffe, v4
	v_cvt_u32_f32_e32 v4, v4
	v_mul_lo_u32 v1, v3, v4
	v_mul_hi_u32 v1, v4, v1
	v_add_u32_e32 v1, v4, v1
	v_mul_hi_u32 v1, v5, v1
	v_mul_lo_u32 v3, v1, v2
	v_sub_u32_e32 v3, v5, v3
	v_add_u32_e32 v4, 1, v1
	v_cmp_ge_u32_e32 vcc, v3, v2
	s_nop 1
	v_cndmask_b32_e32 v1, v1, v4, vcc
	v_sub_u32_e32 v4, v3, v2
	v_cndmask_b32_e32 v3, v3, v4, vcc
	v_add_u32_e32 v4, 1, v1
	v_cmp_ge_u32_e32 vcc, v3, v2
	v_add_u32_e32 v3, 1, v5
	s_nop 0
	v_cndmask_b32_e32 v1, v1, v4, vcc
	v_mul_lo_u32 v4, v2, v1
	v_add_u32_e32 v2, v4, v2
	v_cmp_ne_u32_e32 vcc, v3, v2
	s_and_saveexec_b64 s[14:15], vcc
	s_xor_b64 s[18:19], exec, s[14:15]
	s_cbranch_execz .LBB0_507
	s_waitcnt lgkmcnt(0)
	v_add_u32_e32 v1, 1, v1
	v_mul_lo_u32 v1, v1, v0
	v_mov_b32_e32 v0, 0
	global_load_dword v2, v0, s[26:27] offset:-256 sc1
	s_waitcnt vmcnt(0)
	v_cmp_gt_u32_e32 vcc, v1, v2
	s_and_saveexec_b64 s[38:39], vcc
	s_cbranch_execz .LBB0_506
	s_mov_b32 s5, 1
	s_mov_b64 s[40:41], 0
	s_branch .LBB0_497

; __device__ __forceinline__ unsigned xb_ld(unsigned* p)              { return __hip_atomic_load(p, __ATOMIC_RELAXED, __HIP_MEMORY_SCOPE_AGENT); }
; #define XB_SPIN(cond, bar) do { unsigned _sp = 0; while (cond) { __builtin_amdgcn_s_sleep(1); \
;     if ((++_sp & 255u) == 0u) { if (xb_ld(&(bar)[XB_TMO])) break; if (_sp > XB_SPIN_CAP) { atomicAdd(&(bar)[XB_TMO], 1u); break; } } } } while (0)
; __device__ __forceinline__ void xcd_barrier(const XcdBarrier& b) {
;     ...
;             XB_SPIN(xb_ld(&bar[XB_XGEN(b.x)]) == gen, bar);
.LBB0_499:
	global_load_dword v2, v0, s[26:27] offset:-256 sc1
	s_add_i32 s5, s5, 1
	s_mov_b64 s[46:47], -1
	s_waitcnt vmcnt(0)
	v_cmp_le_u32_e32 vcc, v1, v2
	s_orn2_b64 s[44:45], vcc, exec
	s_branch .LBB0_496

; __device__ __forceinline__ unsigned xb_ld(unsigned* p)              { return __hip_atomic_load(p, __ATOMIC_RELAXED, __HIP_MEMORY_SCOPE_AGENT); }
; __device__ __forceinline__ unsigned xb_add(unsigned* p, unsigned v) { return __hip_atomic_fetch_add(p, v, __ATOMIC_RELAXED, __HIP_MEMORY_SCOPE_AGENT); }
; #define XB_SPIN(cond, bar) do { unsigned _sp = 0; while (cond) { __builtin_amdgcn_s_sleep(1); \
;     if ((++_sp & 255u) == 0u) { if (xb_ld(&(bar)[XB_TMO])) break; if (_sp > XB_SPIN_CAP) { atomicAdd(&(bar)[XB_TMO], 1u); break; } } } } while (0)
; __device__ __forceinline__ void xcd_barrier(const XcdBarrier& b) {
;     ...
;             const unsigned og = xb_add(&bar[XB_TOP], 1u);
;             const unsigned tg = og / nx;
;             if (og + 1u == (tg + 1u) * nx) xb_add(&bar[XB_TOPGEN], 1u);
;             else XB_SPIN(xb_ld(&bar[XB_TOPGEN]) == tg, bar);
.LBB0_510:
	s_or_b64 exec, exec, s[38:39]
	s_waitcnt vmcnt(0)
	v_readfirstlane_b32 s5, v2
	v_cvt_f32_u32_e32 v2, v0
	v_sub_u32_e32 v3, 0, v0
	v_add_u32_e32 v1, s5, v1
	s_mov_b64 s[38:39], -1
	v_rcp_iflag_f32_e32 v2, v2
	s_nop 0
	v_mul_f32_e32 v2, 0x4f7ffffe, v2
	v_cvt_u32_f32_e32 v2, v2
	v_mul_lo_u32 v3, v3, v2
	v_mul_hi_u32 v3, v2, v3
	v_add_u32_e32 v2, v2, v3
	v_mul_hi_u32 v2, v1, v2
	v_mul_lo_u32 v3, v2, v0
	v_sub_u32_e32 v3, v1, v3
	v_cmp_ge_u32_e32 vcc, v3, v0
	v_add_u32_e32 v4, 1, v2
	v_add_u32_e32 v1, 1, v1
	v_cndmask_b32_e32 v2, v2, v4, vcc
	v_sub_u32_e32 v4, v3, v0
	v_cndmask_b32_e32 v3, v3, v4, vcc
	v_cmp_ge_u32_e32 vcc, v3, v0
	v_add_u32_e32 v3, 1, v2
	s_nop 0
	v_cndmask_b32_e32 v2, v2, v3, vcc
	v_mul_lo_u32 v3, v0, v2
	v_add_u32_e32 v0, v3, v0
	v_cmp_ne_u32_e32 vcc, v1, v0
	v_mov_b32_e32 v250, v0
	v_mov_b64_e32 v[0:1], s[26:27]
	s_and_saveexec_b64 s[18:19], vcc
	s_cbranch_execz .LBB0_522
	v_mov_b32_e32 v0, 0
	global_load_dword v1, v0, s[26:27] offset:-256 sc1
	s_mov_b64 s[40:41], 0
	s_waitcnt vmcnt(0)
	v_cmp_gt_u32_e32 vcc, v250, v1
	s_and_saveexec_b64 s[38:39], vcc
	s_cbranch_execz .LBB0_521
	s_mov_b32 s5, 1
	s_branch .LBB0_514

; __device__ __forceinline__ unsigned xb_ld(unsigned* p)              { return __hip_atomic_load(p, __ATOMIC_RELAXED, __HIP_MEMORY_SCOPE_AGENT); }
; #define XB_SPIN(cond, bar) do { unsigned _sp = 0; while (cond) { __builtin_amdgcn_s_sleep(1); \
;     if ((++_sp & 255u) == 0u) { if (xb_ld(&(bar)[XB_TMO])) break; if (_sp > XB_SPIN_CAP) { atomicAdd(&(bar)[XB_TMO], 1u); break; } } } } while (0)
; __device__ __forceinline__ void xcd_barrier(const XcdBarrier& b) {
;     ...
;             else XB_SPIN(xb_ld(&bar[XB_TOPGEN]) == tg, bar);
.LBB0_516:
	global_load_dword v1, v0, s[26:27] offset:-256 sc1
	s_add_i32 s5, s5, 1
	s_mov_b64 s[44:45], -1
	s_waitcnt vmcnt(0)
	v_cmp_le_u32_e32 vcc, v250, v1
	s_orn2_b64 s[48:49], vcc, exec
	s_branch .LBB0_513

; __device__ __forceinline__ unsigned xb_ld(unsigned* p)              { return __hip_atomic_load(p, __ATOMIC_RELAXED, __HIP_MEMORY_SCOPE_AGENT); }
; __device__ __forceinline__ unsigned xb_add(unsigned* p, unsigned v) { return __hip_atomic_fetch_add(p, v, __ATOMIC_RELAXED, __HIP_MEMORY_SCOPE_AGENT); }
; #define XB_SPIN(cond, bar) do { unsigned _sp = 0; while (cond) { __builtin_amdgcn_s_sleep(1); \
;     if ((++_sp & 255u) == 0u) { if (xb_ld(&(bar)[XB_TMO])) break; if (_sp > XB_SPIN_CAP) { atomicAdd(&(bar)[XB_TMO], 1u); break; } } } } while (0)
; __device__ __forceinline__ void xcd_barrier(const XcdBarrier& b) {
;     ...
;         const unsigned old = xb_add(&bar[XB_XSUB(b.x)], 1u);
;         const unsigned gen = old / nloc;
;         if (old + 1u == (gen + 1u) * nloc) {
;             __builtin_amdgcn_fence(__ATOMIC_RELEASE, "agent");
;             asm volatile("s_waitcnt vmcnt(0)" ::: "memory");
;             const unsigned og = xb_add(&bar[XB_TOP], 1u);
;             const unsigned tg = og / nx;
;             if (og + 1u == (tg + 1u) * nx) xb_add(&bar[XB_TOPGEN], 1u);
;             else XB_SPIN(xb_ld(&bar[XB_TOPGEN]) == tg, bar);
;             __builtin_amdgcn_fence(__ATOMIC_ACQUIRE, "agent");
;             xb_add(&bar[XB_XGEN(b.x)], 1u);
;             asm volatile("s_waitcnt vmcnt(0)" ::: "memory");
;         } else {
;             XB_SPIN(xb_ld(&bar[XB_XGEN(b.x)]) == gen, bar);
.LBB0_770:
	s_or_b64 exec, exec, s[4:5]
	v_cvt_f32_u32_e32 v4, v2
	s_waitcnt vmcnt(0)
	v_readfirstlane_b32 s4, v3
	v_sub_u32_e32 v3, 0, v2
	v_rcp_iflag_f32_e32 v4, v4
	v_add_u32_e32 v5, s4, v1
	v_mul_f32_e32 v4, 0x4f7ffffe, v4
	v_cvt_u32_f32_e32 v4, v4
	v_mul_lo_u32 v1, v3, v4
	v_mul_hi_u32 v1, v4, v1
	v_add_u32_e32 v1, v4, v1
	v_mul_hi_u32 v1, v5, v1
	v_mul_lo_u32 v3, v1, v2
	v_sub_u32_e32 v3, v5, v3
	v_add_u32_e32 v4, 1, v1
	v_cmp_ge_u32_e32 vcc, v3, v2
	s_nop 1
	v_cndmask_b32_e32 v1, v1, v4, vcc
	v_sub_u32_e32 v4, v3, v2
	v_cndmask_b32_e32 v3, v3, v4, vcc
	v_add_u32_e32 v4, 1, v1
	v_cmp_ge_u32_e32 vcc, v3, v2
	v_add_u32_e32 v3, 1, v5
	s_nop 0
	v_cndmask_b32_e32 v1, v1, v4, vcc
	v_mul_lo_u32 v4, v2, v1
	v_add_u32_e32 v2, v4, v2
	v_cmp_ne_u32_e32 vcc, v3, v2
	s_and_saveexec_b64 s[4:5], vcc
	s_xor_b64 s[4:5], exec, s[4:5]
	s_cbranch_execz .LBB0_784
	s_waitcnt lgkmcnt(0)
	v_add_u32_e32 v1, 1, v1
	v_mul_lo_u32 v1, v1, v0
	v_mov_b32_e32 v0, 0
	global_load_dword v2, v0, s[26:27] offset:-256 sc1
	s_waitcnt vmcnt(0)
	v_cmp_gt_u32_e32 vcc, v1, v2
	s_and_saveexec_b64 s[18:19], vcc
	s_cbranch_execz .LBB0_783
	s_mov_b32 s16, 1
	s_mov_b64 s[36:37], 0
	s_branch .LBB0_774

; __device__ __forceinline__ unsigned xb_ld(unsigned* p)              { return __hip_atomic_load(p, __ATOMIC_RELAXED, __HIP_MEMORY_SCOPE_AGENT); }
; #define XB_SPIN(cond, bar) do { unsigned _sp = 0; while (cond) { __builtin_amdgcn_s_sleep(1); \
;     if ((++_sp & 255u) == 0u) { if (xb_ld(&(bar)[XB_TMO])) break; if (_sp > XB_SPIN_CAP) { atomicAdd(&(bar)[XB_TMO], 1u); break; } } } } while (0)
; __device__ __forceinline__ void xcd_barrier(const XcdBarrier& b) {
;     ...
;             XB_SPIN(xb_ld(&bar[XB_XGEN(b.x)]) == gen, bar);
.LBB0_776:
	global_load_dword v2, v0, s[26:27] offset:-256 sc1
	s_add_i32 s16, s16, 1
	s_mov_b64 s[42:43], -1
	s_waitcnt vmcnt(0)
	v_cmp_le_u32_e32 vcc, v1, v2
	s_orn2_b64 s[40:41], vcc, exec
	s_branch .LBB0_773

; __device__ __forceinline__ unsigned xb_ld(unsigned* p)              { return __hip_atomic_load(p, __ATOMIC_RELAXED, __HIP_MEMORY_SCOPE_AGENT); }
; __device__ __forceinline__ unsigned xb_add(unsigned* p, unsigned v) { return __hip_atomic_fetch_add(p, v, __ATOMIC_RELAXED, __HIP_MEMORY_SCOPE_AGENT); }
; #define XB_SPIN(cond, bar) do { unsigned _sp = 0; while (cond) { __builtin_amdgcn_s_sleep(1); \
;     if ((++_sp & 255u) == 0u) { if (xb_ld(&(bar)[XB_TMO])) break; if (_sp > XB_SPIN_CAP) { atomicAdd(&(bar)[XB_TMO], 1u); break; } } } } while (0)
; __device__ __forceinline__ void xcd_barrier(const XcdBarrier& b) {
;     ...
;             const unsigned og = xb_add(&bar[XB_TOP], 1u);
;             const unsigned tg = og / nx;
;             if (og + 1u == (tg + 1u) * nx) xb_add(&bar[XB_TOPGEN], 1u);
;             else XB_SPIN(xb_ld(&bar[XB_TOPGEN]) == tg, bar);
.LBB0_787:
	s_or_b64 exec, exec, s[18:19]
	s_waitcnt vmcnt(0)
	v_readfirstlane_b32 s4, v2
	v_cvt_f32_u32_e32 v2, v0
	v_sub_u32_e32 v3, 0, v0
	v_add_u32_e32 v1, s4, v1
	s_mov_b64 s[18:19], -1
	v_rcp_iflag_f32_e32 v2, v2
	s_nop 0
	v_mul_f32_e32 v2, 0x4f7ffffe, v2
	v_cvt_u32_f32_e32 v2, v2
	v_mul_lo_u32 v3, v3, v2
	v_mul_hi_u32 v3, v2, v3
	v_add_u32_e32 v2, v2, v3
	v_mul_hi_u32 v2, v1, v2
	v_mul_lo_u32 v3, v2, v0
	v_sub_u32_e32 v3, v1, v3
	v_cmp_ge_u32_e32 vcc, v3, v0
	v_add_u32_e32 v4, 1, v2
	v_add_u32_e32 v1, 1, v1
	v_cndmask_b32_e32 v2, v2, v4, vcc
	v_sub_u32_e32 v4, v3, v0
	v_cndmask_b32_e32 v3, v3, v4, vcc
	v_cmp_ge_u32_e32 vcc, v3, v0
	v_add_u32_e32 v3, 1, v2
	s_nop 0
	v_cndmask_b32_e32 v2, v2, v3, vcc
	v_mul_lo_u32 v3, v0, v2
	v_add_u32_e32 v0, v3, v0
	v_cmp_ne_u32_e32 vcc, v1, v0
	v_mov_b32_e32 v250, v0
	v_mov_b64_e32 v[0:1], s[26:27]
	s_and_saveexec_b64 s[4:5], vcc
	s_cbranch_execz .LBB0_799
	v_mov_b32_e32 v0, 0
	global_load_dword v1, v0, s[26:27] offset:-256 sc1
	s_mov_b64 s[36:37], 0
	s_waitcnt vmcnt(0)
	v_cmp_gt_u32_e32 vcc, v250, v1
	s_and_saveexec_b64 s[18:19], vcc
	s_cbranch_execz .LBB0_798
	s_mov_b32 s16, 1
	s_branch .LBB0_791

; __device__ __forceinline__ unsigned xb_ld(unsigned* p)              { return __hip_atomic_load(p, __ATOMIC_RELAXED, __HIP_MEMORY_SCOPE_AGENT); }
; #define XB_SPIN(cond, bar) do { unsigned _sp = 0; while (cond) { __builtin_amdgcn_s_sleep(1); \
;     if ((++_sp & 255u) == 0u) { if (xb_ld(&(bar)[XB_TMO])) break; if (_sp > XB_SPIN_CAP) { atomicAdd(&(bar)[XB_TMO], 1u); break; } } } } while (0)
; __device__ __forceinline__ void xcd_barrier(const XcdBarrier& b) {
;     ...
;             else XB_SPIN(xb_ld(&bar[XB_TOPGEN]) == tg, bar);
.LBB0_793:
	global_load_dword v1, v0, s[26:27] offset:-256 sc1
	s_add_i32 s16, s16, 1
	s_mov_b64 s[40:41], -1
	s_waitcnt vmcnt(0)
	v_cmp_le_u32_e32 vcc, v250, v1
	s_orn2_b64 s[44:45], vcc, exec
	s_branch .LBB0_790

; __device__ __forceinline__ unsigned xb_ld(unsigned* p)              { return __hip_atomic_load(p, __ATOMIC_RELAXED, __HIP_MEMORY_SCOPE_AGENT); }
; __device__ __forceinline__ unsigned xb_add(unsigned* p, unsigned v) { return __hip_atomic_fetch_add(p, v, __ATOMIC_RELAXED, __HIP_MEMORY_SCOPE_AGENT); }
; #define XB_SPIN(cond, bar) do { unsigned _sp = 0; while (cond) { __builtin_amdgcn_s_sleep(1); \
;     if ((++_sp & 255u) == 0u) { if (xb_ld(&(bar)[XB_TMO])) break; if (_sp > XB_SPIN_CAP) { atomicAdd(&(bar)[XB_TMO], 1u); break; } } } } while (0)
; __device__ __forceinline__ void xcd_barrier(const XcdBarrier& b) {
;     ...
;         const unsigned old = xb_add(&bar[XB_XSUB(b.x)], 1u);
;         const unsigned gen = old / nloc;
;         if (old + 1u == (gen + 1u) * nloc) {
;             __builtin_amdgcn_fence(__ATOMIC_RELEASE, "agent");
;             asm volatile("s_waitcnt vmcnt(0)" ::: "memory");
;             const unsigned og = xb_add(&bar[XB_TOP], 1u);
;             const unsigned tg = og / nx;
;             if (og + 1u == (tg + 1u) * nx) xb_add(&bar[XB_TOPGEN], 1u);
;             else XB_SPIN(xb_ld(&bar[XB_TOPGEN]) == tg, bar);
;             __builtin_amdgcn_fence(__ATOMIC_ACQUIRE, "agent");
;             xb_add(&bar[XB_XGEN(b.x)], 1u);
;             asm volatile("s_waitcnt vmcnt(0)" ::: "memory");
;         } else {
;             XB_SPIN(xb_ld(&bar[XB_XGEN(b.x)]) == gen, bar);
.LBB0_944:
	s_or_b64 exec, exec, s[4:5]
	v_cvt_f32_u32_e32 v4, v2
	s_waitcnt vmcnt(0)
	v_readfirstlane_b32 s4, v3
	v_sub_u32_e32 v3, 0, v2
	v_rcp_iflag_f32_e32 v4, v4
	v_add_u32_e32 v5, s4, v1
	v_mul_f32_e32 v4, 0x4f7ffffe, v4
	v_cvt_u32_f32_e32 v4, v4
	v_mul_lo_u32 v1, v3, v4
	v_mul_hi_u32 v1, v4, v1
	v_add_u32_e32 v1, v4, v1
	v_mul_hi_u32 v1, v5, v1
	v_mul_lo_u32 v3, v1, v2
	v_sub_u32_e32 v3, v5, v3
	v_add_u32_e32 v4, 1, v1
	v_cmp_ge_u32_e32 vcc, v3, v2
	s_nop 1
	v_cndmask_b32_e32 v1, v1, v4, vcc
	v_sub_u32_e32 v4, v3, v2
	v_cndmask_b32_e32 v3, v3, v4, vcc
	v_add_u32_e32 v4, 1, v1
	v_cmp_ge_u32_e32 vcc, v3, v2
	v_add_u32_e32 v3, 1, v5
	s_nop 0
	v_cndmask_b32_e32 v1, v1, v4, vcc
	v_mul_lo_u32 v4, v2, v1
	v_add_u32_e32 v2, v4, v2
	v_cmp_ne_u32_e32 vcc, v3, v2
	s_and_saveexec_b64 s[4:5], vcc
	s_xor_b64 s[4:5], exec, s[4:5]
	s_cbranch_execz .LBB0_958
	s_waitcnt lgkmcnt(0)
	v_add_u32_e32 v1, 1, v1
	v_mul_lo_u32 v1, v1, v0
	v_mov_b32_e32 v0, 0
	global_load_dword v2, v0, s[26:27] offset:-256 sc1
	s_waitcnt vmcnt(0)
	v_cmp_gt_u32_e32 vcc, v1, v2
	s_and_saveexec_b64 s[14:15], vcc
	s_cbranch_execz .LBB0_957
	s_mov_b64 s[28:29], s[26:27]
	s_mov_b32 s26, 1
	s_mov_b64 s[16:17], 0
	s_branch .LBB0_948

; __device__ __forceinline__ unsigned xb_ld(unsigned* p)              { return __hip_atomic_load(p, __ATOMIC_RELAXED, __HIP_MEMORY_SCOPE_AGENT); }
; #define XB_SPIN(cond, bar) do { unsigned _sp = 0; while (cond) { __builtin_amdgcn_s_sleep(1); \
;     if ((++_sp & 255u) == 0u) { if (xb_ld(&(bar)[XB_TMO])) break; if (_sp > XB_SPIN_CAP) { atomicAdd(&(bar)[XB_TMO], 1u); break; } } } } while (0)
; __device__ __forceinline__ void xcd_barrier(const XcdBarrier& b) {
;     ...
;             XB_SPIN(xb_ld(&bar[XB_XGEN(b.x)]) == gen, bar);
.LBB0_950:
	global_load_dword v2, v0, s[28:29] offset:-256 sc1
	s_add_i32 s26, s26, 1
	s_mov_b64 s[22:23], -1
	s_waitcnt vmcnt(0)
	v_cmp_le_u32_e32 vcc, v1, v2
	s_orn2_b64 s[20:21], vcc, exec
	s_branch .LBB0_947

; __device__ __forceinline__ unsigned xb_ld(unsigned* p)              { return __hip_atomic_load(p, __ATOMIC_RELAXED, __HIP_MEMORY_SCOPE_AGENT); }
; __device__ __forceinline__ unsigned xb_add(unsigned* p, unsigned v) { return __hip_atomic_fetch_add(p, v, __ATOMIC_RELAXED, __HIP_MEMORY_SCOPE_AGENT); }
; #define XB_SPIN(cond, bar) do { unsigned _sp = 0; while (cond) { __builtin_amdgcn_s_sleep(1); \
;     if ((++_sp & 255u) == 0u) { if (xb_ld(&(bar)[XB_TMO])) break; if (_sp > XB_SPIN_CAP) { atomicAdd(&(bar)[XB_TMO], 1u); break; } } } } while (0)
; __device__ __forceinline__ void xcd_barrier(const XcdBarrier& b) {
;     ...
;             const unsigned og = xb_add(&bar[XB_TOP], 1u);
;             const unsigned tg = og / nx;
;             if (og + 1u == (tg + 1u) * nx) xb_add(&bar[XB_TOPGEN], 1u);
;             else XB_SPIN(xb_ld(&bar[XB_TOPGEN]) == tg, bar);
.LBB0_961:
	s_or_b64 exec, exec, s[14:15]
	v_cvt_f32_u32_e32 v3, v0
	s_waitcnt vmcnt(0)
	v_readfirstlane_b32 s4, v2
	s_mov_b64 s[14:15], -1
	v_rcp_iflag_f32_e32 v3, v3
	v_add_u32_e32 v1, s4, v1
	v_add_u32_e32 v4, 1, v1
	v_mul_f32_e32 v2, 0x4f7ffffe, v3
	v_cvt_u32_f32_e32 v2, v2
	v_sub_u32_e32 v3, 0, v0
	v_mul_lo_u32 v3, v3, v2
	v_mul_hi_u32 v3, v2, v3
	v_add_u32_e32 v2, v2, v3
	v_mul_hi_u32 v2, v1, v2
	v_mul_lo_u32 v3, v2, v0
	v_sub_u32_e32 v1, v1, v3
	v_add_u32_e32 v5, 1, v2
	v_cmp_ge_u32_e32 vcc, v1, v0
	v_sub_u32_e32 v3, v1, v0
	s_nop 0
	v_cndmask_b32_e32 v2, v2, v5, vcc
	v_cndmask_b32_e32 v1, v1, v3, vcc
	v_add_u32_e32 v3, 1, v2
	v_cmp_ge_u32_e32 vcc, v1, v0
	s_nop 1
	v_cndmask_b32_e32 v2, v2, v3, vcc
	v_mul_lo_u32 v1, v0, v2
	v_add_u32_e32 v0, v1, v0
	v_cmp_ne_u32_e32 vcc, v4, v0
	v_mov_b32_e32 v250, v0
	v_mov_b64_e32 v[0:1], s[26:27]
	s_and_saveexec_b64 s[4:5], vcc
	s_cbranch_execz .LBB0_973
	v_mov_b32_e32 v0, 0
	global_load_dword v1, v0, s[26:27] offset:-256 sc1
	s_mov_b64 s[16:17], 0
	s_waitcnt vmcnt(0)
	v_cmp_gt_u32_e32 vcc, v250, v1
	s_and_saveexec_b64 s[14:15], vcc
	s_cbranch_execz .LBB0_972
	s_mov_b64 s[28:29], s[26:27]
	s_mov_b32 s26, 1
	s_branch .LBB0_965

; __device__ __forceinline__ unsigned xb_ld(unsigned* p)              { return __hip_atomic_load(p, __ATOMIC_RELAXED, __HIP_MEMORY_SCOPE_AGENT); }
; #define XB_SPIN(cond, bar) do { unsigned _sp = 0; while (cond) { __builtin_amdgcn_s_sleep(1); \
;     if ((++_sp & 255u) == 0u) { if (xb_ld(&(bar)[XB_TMO])) break; if (_sp > XB_SPIN_CAP) { atomicAdd(&(bar)[XB_TMO], 1u); break; } } } } while (0)
; __device__ __forceinline__ void xcd_barrier(const XcdBarrier& b) {
;     ...
;             else XB_SPIN(xb_ld(&bar[XB_TOPGEN]) == tg, bar);
.LBB0_967:
	global_load_dword v1, v0, s[28:29] offset:-256 sc1
	s_add_i32 s26, s26, 1
	s_mov_b64 s[20:21], -1
	s_waitcnt vmcnt(0)
	v_cmp_le_u32_e32 vcc, v250, v1
	s_orn2_b64 s[24:25], vcc, exec
	s_branch .LBB0_964
